# packed-f32 SSD conv + static priority for full conv waves, on top of corrected scan-wave waits and widened Y stores
# baseline (speedup 1.0000x reference)
; __device__ __forceinline__ void ssd_item(const Params& p, LAS unsigned char* lds, int bl, int head, int dry) {
;     ...
;         if (cact) {
;             if (c == 0 && rg == 0) { raw[0] = (u32x2){0u, 0u}; raw[1] = (u32x2){0u, 0u}; raw[2] = (u32x2){0u, 0u}; }
; #pragma unroll
;             for (int seg = 0; seg < 4; ++seg) {
.Ldt_skip:
	v_mov_b32_e32 v16, 0
	s_and_saveexec_b64 s[56:57], s[40:41]
	s_cbranch_execz .LBB0_242
	s_cmp_lt_u32 s98, 4
	s_cbranch_scc1 .Lcw_prio
	s_waitcnt vmcnt(6)
	s_branch .Lcw_skip
